# SSD conv step of the sample rows (end of P2b) hand-written: all loads up front, scalar row addressing, spread over all 256 workgroups
# speedup vs baseline: 1.0137x; 1.0030x over previous
; __device__ __forceinline__ float siluf_(float x) { return x * __builtin_amdgcn_rcpf(1.f + __expf(-x)); }
; template <int NT, bool SAMPLE>
; __device__ __forceinline__ void ssdconv_item(const bf16_t* PROJ, int row0, bool has_hist, const float* st, int cgi, const float* w, const float* bias, bf16_t* XBC, float* state_out) {
;     const int c0 = cgi * 8;
;     float wv[4][8], bv[8], h0[8], h1[8], h2[8];
; #pragma unroll
;     for (int i = 0; i < 4; ++i) { const f32x4 a = *(const f32x4*)(w + i * XBCW + c0), b = *(const f32x4*)(w + i * XBCW + c0 + 4);
;         wv[i][0] = a.x; wv[i][1] = a.y; wv[i][2] = a.z; wv[i][3] = a.w; wv[i][4] = b.x; wv[i][5] = b.y; wv[i][6] = b.z; wv[i][7] = b.w; }
;     { const f32x4 a = *(const f32x4*)(bias + c0), b = *(const f32x4*)(bias + c0 + 4);
;       bv[0] = a.x; bv[1] = a.y; bv[2] = a.z; bv[3] = a.w; bv[4] = b.x; bv[5] = b.y; bv[6] = b.z; bv[7] = b.w; }
;     if (SAMPLE) {
; #pragma unroll
;         for (int e = 0; e < 8; ++e) { h0[e] = st[0 * XBCW + c0 + e]; h1[e] = st[1 * XBCW + c0 + e]; h2[e] = st[2 * XBCW + c0 + e]; }
;     } else if (has_hist) {
;         unpack8(*(const u32x4*)(PROJ + (size_t)(row0 - 3) * NPROJ + CXBC + c0), h0);
;         unpack8(*(const u32x4*)(PROJ + (size_t)(row0 - 2) * NPROJ + CXBC + c0), h1);
;         unpack8(*(const u32x4*)(PROJ + (size_t)(row0 - 1) * NPROJ + CXBC + c0), h2);
;     } else {
; #pragma unroll
;         for (int e = 0; e < 8; ++e) { h0[e] = 0.f; h1[e] = 0.f; h2[e] = 0.f; }
;     }
;     u32x4 rows[NT];
; #pragma unroll
;     for (int t = 0; t < NT; ++t) rows[t] = *(const u32x4*)(PROJ + (size_t)(row0 + t) * NPROJ + CXBC + c0);
; #pragma unroll
;     for (int t = 0; t < NT; ++t) {
;         float cur[8], o[8];
;         unpack8(rows[t], cur);
; #pragma unroll
;         for (int e = 0; e < 8; ++e) { float v = h0[e] * wv[0][e] + h1[e] * wv[1][e] + h2[e] * wv[2][e] + cur[e] * wv[3][e] + bv[e]; o[e] = siluf_(v); h0[e] = h1[e]; h1[e] = h2[e]; h2[e] = cur[e]; }
;         *(u32x4*)(XBC + (size_t)(row0 + t) * XBCW + c0) = pack8(o);
.LBB0_365:
	s_or_b64 exec, exec, s[0:1]
	v_readlane_b32 s4, v253, 2
	s_load_dwordx2 s[6:7], s[22:23], 0x18
	s_load_dwordx4 s[8:11], s[22:23], 0x40
	v_cmp_gt_u32_e32 vcc, 192, v212
	s_and_saveexec_b64 s[0:1], vcc
	s_cbranch_execz .Lp2s_end
	s_lshr_b32 s5, s4, 1
	s_and_b32 s4, s4, 1
	s_mul_i32 s4, s4, 192
	v_add_u32_e32 v0, s4, v212
	v_lshlrev_b32_e32 v1, 4, v0
	v_lshlrev_b32_e32 v2, 5, v0
	s_waitcnt lgkmcnt(0)
	s_mov_b32 s24, s8
	s_mov_b32 s25, s9
	global_load_dwordx4 v[8:11], v2, s[24:25]
	global_load_dwordx4 v[12:15], v2, s[24:25] offset:16
	s_add_u32 s24, s24, 0x3000
	s_addc_u32 s25, s25, 0
	global_load_dwordx4 v[16:19], v2, s[24:25]
	global_load_dwordx4 v[20:23], v2, s[24:25] offset:16
	s_add_u32 s24, s24, 0x3000
	s_addc_u32 s25, s25, 0
	global_load_dwordx4 v[24:27], v2, s[24:25]
	global_load_dwordx4 v[28:31], v2, s[24:25] offset:16
	s_add_u32 s24, s24, 0x3000
	s_addc_u32 s25, s25, 0
	global_load_dwordx4 v[32:35], v2, s[24:25]
	global_load_dwordx4 v[36:39], v2, s[24:25] offset:16
	global_load_dwordx4 v[40:43], v2, s[10:11]
	global_load_dwordx4 v[44:47], v2, s[10:11] offset:16
	s_mul_i32 s12, s5, 0x9000
	s_add_u32 s24, s6, s12
	s_addc_u32 s25, s7, 0
	global_load_dwordx4 v[48:51], v2, s[24:25]
	global_load_dwordx4 v[52:55], v2, s[24:25] offset:16
	s_add_u32 s24, s24, 0x3000
	s_addc_u32 s25, s25, 0
	global_load_dwordx4 v[56:59], v2, s[24:25]
	global_load_dwordx4 v[60:63], v2, s[24:25] offset:16
	s_add_u32 s24, s24, 0x3000
	s_addc_u32 s25, s25, 0
	global_load_dwordx4 v[64:67], v2, s[24:25]
	global_load_dwordx4 v[68:71], v2, s[24:25] offset:16
	s_mul_i32 s13, s5, 0x12800
	s_add_u32 s24, s18, 0x9890000
	s_addc_u32 s25, s19, 0
	s_add_u32 s24, s24, s13
	s_addc_u32 s25, s25, 0
	s_add_u32 s24, s24, 0x9401000
	s_addc_u32 s25, s25, 0
	global_load_dwordx4 v[72:75], v1, s[24:25]
	s_add_u32 s24, s24, 0x4a00
	s_addc_u32 s25, s25, 0
	global_load_dwordx4 v[76:79], v1, s[24:25]
	s_add_u32 s24, s24, 0x4a00
	s_addc_u32 s25, s25, 0
	global_load_dwordx4 v[80:83], v1, s[24:25]
	s_add_u32 s24, s24, 0x4a00
	s_addc_u32 s25, s25, 0
	global_load_dwordx4 v[84:87], v1, s[24:25]
	s_mul_i32 s13, s5, 0x6000
	s_add_u32 s24, s18, 0x135d0000
	s_addc_u32 s25, s19, 0
	s_add_u32 s24, s24, s13
	s_addc_u32 s25, s25, 0
	s_add_u32 s24, s24, 0x3000000
	s_addc_u32 s25, s25, 0
	s_waitcnt vmcnt(0)
	v_lshlrev_b32_e32 v88, 16, v72
	v_and_b32_e32 v89, 0xffff0000, v72
	v_lshlrev_b32_e32 v90, 16, v73
	v_and_b32_e32 v91, 0xffff0000, v73
	v_lshlrev_b32_e32 v92, 16, v74
	v_and_b32_e32 v93, 0xffff0000, v74
	v_lshlrev_b32_e32 v94, 16, v75
	v_and_b32_e32 v95, 0xffff0000, v75
	v_pk_mul_f32 v[96:97], v[48:49], v[8:9]
	v_pk_fma_f32 v[96:97], v[56:57], v[16:17], v[96:97]
	v_pk_fma_f32 v[96:97], v[64:65], v[24:25], v[96:97]
	v_pk_fma_f32 v[96:97], v[88:89], v[32:33], v[96:97]
	v_pk_add_f32 v[96:97], v[96:97], v[40:41]
	v_pk_mul_f32 v[98:99], v[50:51], v[10:11]
	v_pk_fma_f32 v[98:99], v[58:59], v[18:19], v[98:99]
	v_pk_fma_f32 v[98:99], v[66:67], v[26:27], v[98:99]
	v_pk_fma_f32 v[98:99], v[90:91], v[34:35], v[98:99]
	v_pk_add_f32 v[98:99], v[98:99], v[42:43]
	v_pk_mul_f32 v[100:101], v[52:53], v[12:13]
	v_pk_fma_f32 v[100:101], v[60:61], v[20:21], v[100:101]
	v_pk_fma_f32 v[100:101], v[68:69], v[28:29], v[100:101]
	v_pk_fma_f32 v[100:101], v[92:93], v[36:37], v[100:101]
	v_pk_add_f32 v[100:101], v[100:101], v[44:45]
	v_pk_mul_f32 v[102:103], v[54:55], v[14:15]
	v_pk_fma_f32 v[102:103], v[62:63], v[22:23], v[102:103]
	v_pk_fma_f32 v[102:103], v[70:71], v[30:31], v[102:103]
	v_pk_fma_f32 v[102:103], v[94:95], v[38:39], v[102:103]
	v_pk_add_f32 v[102:103], v[102:103], v[46:47]
	v_mul_f32_e32 v104, 0xbfb8aa3b, v96
	v_mul_f32_e32 v105, 0xbfb8aa3b, v97
	v_mul_f32_e32 v106, 0xbfb8aa3b, v98
	v_mul_f32_e32 v107, 0xbfb8aa3b, v99
	v_mul_f32_e32 v108, 0xbfb8aa3b, v100
	v_mul_f32_e32 v109, 0xbfb8aa3b, v101
	v_mul_f32_e32 v110, 0xbfb8aa3b, v102
	v_mul_f32_e32 v111, 0xbfb8aa3b, v103
	v_exp_f32_e32 v104, v104
	v_exp_f32_e32 v105, v105
	v_exp_f32_e32 v106, v106
	v_exp_f32_e32 v107, v107
	v_exp_f32_e32 v108, v108
	v_exp_f32_e32 v109, v109
	v_exp_f32_e32 v110, v110
	v_exp_f32_e32 v111, v111
	v_add_f32_e32 v104, 1.0, v104
	v_add_f32_e32 v105, 1.0, v105
	v_add_f32_e32 v106, 1.0, v106
	v_add_f32_e32 v107, 1.0, v107
	v_add_f32_e32 v108, 1.0, v108
	v_add_f32_e32 v109, 1.0, v109
	v_add_f32_e32 v110, 1.0, v110
	v_add_f32_e32 v111, 1.0, v111
	v_rcp_f32_e32 v104, v104
	v_rcp_f32_e32 v105, v105
	v_rcp_f32_e32 v106, v106
	v_rcp_f32_e32 v107, v107
	v_rcp_f32_e32 v108, v108
	v_rcp_f32_e32 v109, v109
	v_rcp_f32_e32 v110, v110
	v_rcp_f32_e32 v111, v111
	v_mul_f32_e32 v104, v96, v104
	v_mul_f32_e32 v105, v97, v105
	v_mul_f32_e32 v106, v98, v106
	v_mul_f32_e32 v107, v99, v107
	v_mul_f32_e32 v108, v100, v108
	v_mul_f32_e32 v109, v101, v109
	v_mul_f32_e32 v110, v102, v110
	v_mul_f32_e32 v111, v103, v111
	v_cvt_pk_bf16_f32 v112, v104, v105
	v_cvt_pk_bf16_f32 v113, v106, v107
	v_cvt_pk_bf16_f32 v114, v108, v109
	v_cvt_pk_bf16_f32 v115, v110, v111
	global_store_dwordx4 v1, v[112:115], s[24:25]
	s_add_u32 s24, s24, 0x1800
	s_addc_u32 s25, s25, 0
	v_lshlrev_b32_e32 v48, 16, v76
	v_and_b32_e32 v49, 0xffff0000, v76
	v_lshlrev_b32_e32 v50, 16, v77
	v_and_b32_e32 v51, 0xffff0000, v77
	v_lshlrev_b32_e32 v52, 16, v78
	v_and_b32_e32 v53, 0xffff0000, v78
	v_lshlrev_b32_e32 v54, 16, v79
	v_and_b32_e32 v55, 0xffff0000, v79
	v_pk_mul_f32 v[96:97], v[56:57], v[8:9]
	v_pk_fma_f32 v[96:97], v[64:65], v[16:17], v[96:97]
	v_pk_fma_f32 v[96:97], v[88:89], v[24:25], v[96:97]
	v_pk_fma_f32 v[96:97], v[48:49], v[32:33], v[96:97]
	v_pk_add_f32 v[96:97], v[96:97], v[40:41]
	v_pk_mul_f32 v[98:99], v[58:59], v[10:11]
	v_pk_fma_f32 v[98:99], v[66:67], v[18:19], v[98:99]
; __device__ __forceinline__ float siluf_(float x) { return x * __builtin_amdgcn_rcpf(1.f + __expf(-x)); }
; template <int NT, bool SAMPLE>
; __device__ __forceinline__ void ssdconv_item(const bf16_t* PROJ, int row0, bool has_hist, const float* st, int cgi, const float* w, const float* bias, bf16_t* XBC, float* state_out) {
;     ...
; #pragma unroll
;     for (int t = 0; t < NT; ++t) {
;         float cur[8], o[8];
;         unpack8(rows[t], cur);
; #pragma unroll
;         for (int e = 0; e < 8; ++e) { float v = h0[e] * wv[0][e] + h1[e] * wv[1][e] + h2[e] * wv[2][e] + cur[e] * wv[3][e] + bv[e]; o[e] = siluf_(v); h0[e] = h1[e]; h1[e] = h2[e]; h2[e] = cur[e]; }
;         *(u32x4*)(XBC + (size_t)(row0 + t) * XBCW + c0) = pack8(o);
	v_pk_fma_f32 v[98:99], v[90:91], v[26:27], v[98:99]
	v_pk_fma_f32 v[98:99], v[50:51], v[34:35], v[98:99]
	v_pk_add_f32 v[98:99], v[98:99], v[42:43]
	v_pk_mul_f32 v[100:101], v[60:61], v[12:13]
	v_pk_fma_f32 v[100:101], v[68:69], v[20:21], v[100:101]
	v_pk_fma_f32 v[100:101], v[92:93], v[28:29], v[100:101]
	v_pk_fma_f32 v[100:101], v[52:53], v[36:37], v[100:101]
	v_pk_add_f32 v[100:101], v[100:101], v[44:45]
	v_pk_mul_f32 v[102:103], v[62:63], v[14:15]
	v_pk_fma_f32 v[102:103], v[70:71], v[22:23], v[102:103]
	v_pk_fma_f32 v[102:103], v[94:95], v[30:31], v[102:103]
	v_pk_fma_f32 v[102:103], v[54:55], v[38:39], v[102:103]
	v_pk_add_f32 v[102:103], v[102:103], v[46:47]
	v_mul_f32_e32 v104, 0xbfb8aa3b, v96
	v_mul_f32_e32 v105, 0xbfb8aa3b, v97
	v_mul_f32_e32 v106, 0xbfb8aa3b, v98
	v_mul_f32_e32 v107, 0xbfb8aa3b, v99
	v_mul_f32_e32 v108, 0xbfb8aa3b, v100
	v_mul_f32_e32 v109, 0xbfb8aa3b, v101
	v_mul_f32_e32 v110, 0xbfb8aa3b, v102
	v_mul_f32_e32 v111, 0xbfb8aa3b, v103
	v_exp_f32_e32 v104, v104
	v_exp_f32_e32 v105, v105
	v_exp_f32_e32 v106, v106
	v_exp_f32_e32 v107, v107
	v_exp_f32_e32 v108, v108
	v_exp_f32_e32 v109, v109
	v_exp_f32_e32 v110, v110
	v_exp_f32_e32 v111, v111
	v_add_f32_e32 v104, 1.0, v104
	v_add_f32_e32 v105, 1.0, v105
	v_add_f32_e32 v106, 1.0, v106
	v_add_f32_e32 v107, 1.0, v107
	v_add_f32_e32 v108, 1.0, v108
	v_add_f32_e32 v109, 1.0, v109
	v_add_f32_e32 v110, 1.0, v110
	v_add_f32_e32 v111, 1.0, v111
	v_rcp_f32_e32 v104, v104
	v_rcp_f32_e32 v105, v105
	v_rcp_f32_e32 v106, v106
	v_rcp_f32_e32 v107, v107
	v_rcp_f32_e32 v108, v108
	v_rcp_f32_e32 v109, v109
	v_rcp_f32_e32 v110, v110
	v_rcp_f32_e32 v111, v111
	v_mul_f32_e32 v104, v96, v104
	v_mul_f32_e32 v105, v97, v105
	v_mul_f32_e32 v106, v98, v106
	v_mul_f32_e32 v107, v99, v107
	v_mul_f32_e32 v108, v100, v108
	v_mul_f32_e32 v109, v101, v109
	v_mul_f32_e32 v110, v102, v110
	v_mul_f32_e32 v111, v103, v111
	v_cvt_pk_bf16_f32 v112, v104, v105
	v_cvt_pk_bf16_f32 v113, v106, v107
	v_cvt_pk_bf16_f32 v114, v108, v109
	v_cvt_pk_bf16_f32 v115, v110, v111
	global_store_dwordx4 v1, v[112:115], s[24:25]
	s_add_u32 s24, s24, 0x1800
	s_addc_u32 s25, s25, 0
	v_lshlrev_b32_e32 v56, 16, v80
	v_and_b32_e32 v57, 0xffff0000, v80
	v_lshlrev_b32_e32 v58, 16, v81
	v_and_b32_e32 v59, 0xffff0000, v81
	v_lshlrev_b32_e32 v60, 16, v82
	v_and_b32_e32 v61, 0xffff0000, v82
	v_lshlrev_b32_e32 v62, 16, v83
	v_and_b32_e32 v63, 0xffff0000, v83
	v_pk_mul_f32 v[96:97], v[64:65], v[8:9]
	v_pk_fma_f32 v[96:97], v[88:89], v[16:17], v[96:97]
	v_pk_fma_f32 v[96:97], v[48:49], v[24:25], v[96:97]
	v_pk_fma_f32 v[96:97], v[56:57], v[32:33], v[96:97]
	v_pk_add_f32 v[96:97], v[96:97], v[40:41]
	v_pk_mul_f32 v[98:99], v[66:67], v[10:11]
	v_pk_fma_f32 v[98:99], v[90:91], v[18:19], v[98:99]
	v_pk_fma_f32 v[98:99], v[50:51], v[26:27], v[98:99]
	v_pk_fma_f32 v[98:99], v[58:59], v[34:35], v[98:99]
	v_pk_add_f32 v[98:99], v[98:99], v[42:43]
	v_pk_mul_f32 v[100:101], v[68:69], v[12:13]
	v_pk_fma_f32 v[100:101], v[92:93], v[20:21], v[100:101]
	v_pk_fma_f32 v[100:101], v[52:53], v[28:29], v[100:101]
	v_pk_fma_f32 v[100:101], v[60:61], v[36:37], v[100:101]
	v_pk_add_f32 v[100:101], v[100:101], v[44:45]
	v_pk_mul_f32 v[102:103], v[70:71], v[14:15]
	v_pk_fma_f32 v[102:103], v[94:95], v[22:23], v[102:103]
	v_pk_fma_f32 v[102:103], v[54:55], v[30:31], v[102:103]
	v_pk_fma_f32 v[102:103], v[62:63], v[38:39], v[102:103]
	v_pk_add_f32 v[102:103], v[102:103], v[46:47]
	v_mul_f32_e32 v104, 0xbfb8aa3b, v96
	v_mul_f32_e32 v105, 0xbfb8aa3b, v97
	v_mul_f32_e32 v106, 0xbfb8aa3b, v98
	v_mul_f32_e32 v107, 0xbfb8aa3b, v99
	v_mul_f32_e32 v108, 0xbfb8aa3b, v100
	v_mul_f32_e32 v109, 0xbfb8aa3b, v101
	v_mul_f32_e32 v110, 0xbfb8aa3b, v102
	v_mul_f32_e32 v111, 0xbfb8aa3b, v103
	v_exp_f32_e32 v104, v104
	v_exp_f32_e32 v105, v105
	v_exp_f32_e32 v106, v106
	v_exp_f32_e32 v107, v107
	v_exp_f32_e32 v108, v108
	v_exp_f32_e32 v109, v109
	v_exp_f32_e32 v110, v110
	v_exp_f32_e32 v111, v111
	v_add_f32_e32 v104, 1.0, v104
	v_add_f32_e32 v105, 1.0, v105
	v_add_f32_e32 v106, 1.0, v106
	v_add_f32_e32 v107, 1.0, v107
; __device__ __forceinline__ float siluf_(float x) { return x * __builtin_amdgcn_rcpf(1.f + __expf(-x)); }
; template <int NT, bool SAMPLE>
; __device__ __forceinline__ void ssdconv_item(const bf16_t* PROJ, int row0, bool has_hist, const float* st, int cgi, const float* w, const float* bias, bf16_t* XBC, float* state_out) {
;     ...
; #pragma unroll
;     for (int t = 0; t < NT; ++t) {
;         float cur[8], o[8];
;         unpack8(rows[t], cur);
; #pragma unroll
;         for (int e = 0; e < 8; ++e) { float v = h0[e] * wv[0][e] + h1[e] * wv[1][e] + h2[e] * wv[2][e] + cur[e] * wv[3][e] + bv[e]; o[e] = siluf_(v); h0[e] = h1[e]; h1[e] = h2[e]; h2[e] = cur[e]; }
;         *(u32x4*)(XBC + (size_t)(row0 + t) * XBCW + c0) = pack8(o);
;     }
;     if (state_out) {
;         *(f32x4*)(state_out + 0 * XBCW + c0) = (f32x4){h0[0], h0[1], h0[2], h0[3]}; *(f32x4*)(state_out + 0 * XBCW + c0 + 4) = (f32x4){h0[4], h0[5], h0[6], h0[7]};
;         *(f32x4*)(state_out + 1 * XBCW + c0) = (f32x4){h1[0], h1[1], h1[2], h1[3]}; *(f32x4*)(state_out + 1 * XBCW + c0 + 4) = (f32x4){h1[4], h1[5], h1[6], h1[7]};
;         *(f32x4*)(state_out + 2 * XBCW + c0) = (f32x4){h2[0], h2[1], h2[2], h2[3]}; *(f32x4*)(state_out + 2 * XBCW + c0 + 4) = (f32x4){h2[4], h2[5], h2[6], h2[7]};
	v_add_f32_e32 v108, 1.0, v108
	v_add_f32_e32 v109, 1.0, v109
	v_add_f32_e32 v110, 1.0, v110
	v_add_f32_e32 v111, 1.0, v111
	v_rcp_f32_e32 v104, v104
	v_rcp_f32_e32 v105, v105
	v_rcp_f32_e32 v106, v106
	v_rcp_f32_e32 v107, v107
	v_rcp_f32_e32 v108, v108
	v_rcp_f32_e32 v109, v109
	v_rcp_f32_e32 v110, v110
	v_rcp_f32_e32 v111, v111
	v_mul_f32_e32 v104, v96, v104
	v_mul_f32_e32 v105, v97, v105
	v_mul_f32_e32 v106, v98, v106
	v_mul_f32_e32 v107, v99, v107
	v_mul_f32_e32 v108, v100, v108
	v_mul_f32_e32 v109, v101, v109
	v_mul_f32_e32 v110, v102, v110
	v_mul_f32_e32 v111, v103, v111
	v_cvt_pk_bf16_f32 v112, v104, v105
	v_cvt_pk_bf16_f32 v113, v106, v107
	v_cvt_pk_bf16_f32 v114, v108, v109
	v_cvt_pk_bf16_f32 v115, v110, v111
	global_store_dwordx4 v1, v[112:115], s[24:25]
	s_add_u32 s24, s24, 0x1800
	s_addc_u32 s25, s25, 0
	v_lshlrev_b32_e32 v64, 16, v84
	v_and_b32_e32 v65, 0xffff0000, v84
	v_lshlrev_b32_e32 v66, 16, v85
	v_and_b32_e32 v67, 0xffff0000, v85
	v_lshlrev_b32_e32 v68, 16, v86
	v_and_b32_e32 v69, 0xffff0000, v86
	v_lshlrev_b32_e32 v70, 16, v87
	v_and_b32_e32 v71, 0xffff0000, v87
	v_pk_mul_f32 v[96:97], v[88:89], v[8:9]
	v_pk_fma_f32 v[96:97], v[48:49], v[16:17], v[96:97]
	v_pk_fma_f32 v[96:97], v[56:57], v[24:25], v[96:97]
	v_pk_fma_f32 v[96:97], v[64:65], v[32:33], v[96:97]
	v_pk_add_f32 v[96:97], v[96:97], v[40:41]
	v_pk_mul_f32 v[98:99], v[90:91], v[10:11]
	v_pk_fma_f32 v[98:99], v[50:51], v[18:19], v[98:99]
	v_pk_fma_f32 v[98:99], v[58:59], v[26:27], v[98:99]
	v_pk_fma_f32 v[98:99], v[66:67], v[34:35], v[98:99]
	v_pk_add_f32 v[98:99], v[98:99], v[42:43]
	v_pk_mul_f32 v[100:101], v[92:93], v[12:13]
	v_pk_fma_f32 v[100:101], v[52:53], v[20:21], v[100:101]
	v_pk_fma_f32 v[100:101], v[60:61], v[28:29], v[100:101]
	v_pk_fma_f32 v[100:101], v[68:69], v[36:37], v[100:101]
	v_pk_add_f32 v[100:101], v[100:101], v[44:45]
	v_pk_mul_f32 v[102:103], v[94:95], v[14:15]
	v_pk_fma_f32 v[102:103], v[54:55], v[22:23], v[102:103]
	v_pk_fma_f32 v[102:103], v[62:63], v[30:31], v[102:103]
	v_pk_fma_f32 v[102:103], v[70:71], v[38:39], v[102:103]
	v_pk_add_f32 v[102:103], v[102:103], v[46:47]
	v_mul_f32_e32 v104, 0xbfb8aa3b, v96
	v_mul_f32_e32 v105, 0xbfb8aa3b, v97
	v_mul_f32_e32 v106, 0xbfb8aa3b, v98
	v_mul_f32_e32 v107, 0xbfb8aa3b, v99
	v_mul_f32_e32 v108, 0xbfb8aa3b, v100
	v_mul_f32_e32 v109, 0xbfb8aa3b, v101
	v_mul_f32_e32 v110, 0xbfb8aa3b, v102
	v_mul_f32_e32 v111, 0xbfb8aa3b, v103
	v_exp_f32_e32 v104, v104
	v_exp_f32_e32 v105, v105
	v_exp_f32_e32 v106, v106
	v_exp_f32_e32 v107, v107
	v_exp_f32_e32 v108, v108
	v_exp_f32_e32 v109, v109
	v_exp_f32_e32 v110, v110
	v_exp_f32_e32 v111, v111
	v_add_f32_e32 v104, 1.0, v104
	v_add_f32_e32 v105, 1.0, v105
	v_add_f32_e32 v106, 1.0, v106
	v_add_f32_e32 v107, 1.0, v107
	v_add_f32_e32 v108, 1.0, v108
	v_add_f32_e32 v109, 1.0, v109
	v_add_f32_e32 v110, 1.0, v110
	v_add_f32_e32 v111, 1.0, v111
	v_rcp_f32_e32 v104, v104
	v_rcp_f32_e32 v105, v105
	v_rcp_f32_e32 v106, v106
	v_rcp_f32_e32 v107, v107
	v_rcp_f32_e32 v108, v108
	v_rcp_f32_e32 v109, v109
	v_rcp_f32_e32 v110, v110
	v_rcp_f32_e32 v111, v111
	v_mul_f32_e32 v104, v96, v104
	v_mul_f32_e32 v105, v97, v105
	v_mul_f32_e32 v106, v98, v106
	v_mul_f32_e32 v107, v99, v107
	v_mul_f32_e32 v108, v100, v108
	v_mul_f32_e32 v109, v101, v109
	v_mul_f32_e32 v110, v102, v110
	v_mul_f32_e32 v111, v103, v111
	v_cvt_pk_bf16_f32 v112, v104, v105
	v_cvt_pk_bf16_f32 v113, v106, v107
	v_cvt_pk_bf16_f32 v114, v108, v109
	v_cvt_pk_bf16_f32 v115, v110, v111
	global_store_dwordx4 v1, v[112:115], s[24:25]
	s_add_u32 s24, s16, 0xc96a000
	s_addc_u32 s25, s17, 0
	s_add_u32 s24, s24, s12
	s_addc_u32 s25, s25, 0
	global_store_dwordx4 v2, v[48:51], s[24:25]
	global_store_dwordx4 v2, v[52:55], s[24:25] offset:16
	s_add_u32 s24, s24, 0x3000
	s_addc_u32 s25, s25, 0
	global_store_dwordx4 v2, v[56:59], s[24:25]
	global_store_dwordx4 v2, v[60:63], s[24:25] offset:16
	s_add_u32 s24, s24, 0x3000
	s_addc_u32 s25, s25, 0
	global_store_dwordx4 v2, v[64:67], s[24:25]
	global_store_dwordx4 v2, v[68:71], s[24:25] offset:16
